# P1c: counted vmcnt(10) before BAR_a(7) so the early B0 fragment reads are covered by a wait+barrier (robustness, no schedule change)
# speedup vs baseline: 1.0078x; 1.0078x over previous
; #define G_STAGE(bufoff, gbase, voff) do { _Pragma("unroll") for (int _i = 0; _i < 2; ++_i) \
;         __builtin_amdgcn_global_load_lds((const unsigned*)((const char*)(gbase) + (voff)[_i]), (LAS unsigned*)(lds + (bufoff) + ldsw + _i * 8192), 16, 0, 0); } while (0)
; #define G_WAIT_V(n) asm volatile("s_waitcnt vmcnt(" #n ")" ::: "memory")
; #define G_WAIT_L(n) asm volatile("s_waitcnt lgkmcnt(" #n ")" ::: "memory")
; #define G_BAR __builtin_amdgcn_s_barrier()
; #define G_SCHED __builtin_amdgcn_sched_barrier(0)
; template <int MODE  , class Epi, class Sched>
; __device__ __forceinline__ void gemm_phase(LAS unsigned char* lds, const GemmDesc g, const Sched& S, const Epi& E) {
;     ...
;             const bool last = (t == nt - 2);
;             const char* a1 = cA + (size_t)(t + 1) * kstep;
;             const char* a2 = last ? nA : cA + (size_t)(t + 2) * kstep; const char* b2 = last ? nB : cB + (size_t)(t + 2) * kstep;
;             const char* a3 = a2 + kstep; const char* b3 = b2 + kstep;
;             G_LDB(B0, 0, 0); G_SCHED; G_LDA(At, 0, 0); G_STAGE(G_SA(1, 1), a1 + hstepA, voffA);
;             G_WAIT_L(8); G_BAR; G_WAIT_L(0); G_MMA(0, 0, At, B0); G_BAR; G_SCHED;
;             G_LDB(B1, 0, 1); G_STAGE(G_SB(0, 0), b2, voffB);
;             G_BAR; G_WAIT_L(0); G_MMA(0, 1, At, B1); G_BAR;
;             G_LDA(At, 0, 1); G_STAGE(G_SA(0, 0), a2, voffA);
;             G_BAR; G_WAIT_L(0); G_MMA(1, 0, At, B0); G_BAR; G_SCHED;
;             G_STAGE(G_SB(0, 1), b2 + hstepB, voffB);
;             G_WAIT_V(6); G_BAR; G_MMA(1, 1, At, B1); G_BAR;
.Lnodb_p1c:
.LBB0_527:
	s_add_u32 s40, s34, 0x100
	s_addc_u32 s41, s35, 0
	s_cmp_eq_u32 s77, 12
	s_cselect_b32 s47, s21, s41
	s_cselect_b32 s46, s20, s40
	s_cselect_b32 s45, s3, s76
	s_cselect_b32 s44, s2, s72
	s_mov_b32 m0, s64
	s_add_u32 s98, s34, 0x44080
	s_addc_u32 s99, s35, 0
	ds_read_b128 v[162:165], v194
	ds_read_b128 v[166:169], v194 offset:1024
	ds_read_b128 v[170:173], v194 offset:2048
	ds_read_b128 v[174:177], v194 offset:3072
	ds_read_b128 v[178:181], v194 offset:4096
	ds_read_b128 v[182:185], v194 offset:5120
	ds_read_b128 v[186:189], v194 offset:6144
	ds_read_b128 v[198:201], v194 offset:7168
	global_load_lds_dwordx4 v146, s[98:99]
	s_mov_b32 m0, s65
	s_nop 0
	global_load_lds_dwordx4 v150, s[98:99]
	s_waitcnt lgkmcnt(8)
	s_barrier
	s_waitcnt lgkmcnt(0)
	s_setprio 1
	s_waitcnt lgkmcnt(0)
	v_mfma_i32_16x16x64_i8 v[134:137], v[232:235], v[162:165], v[134:137]
	v_mfma_i32_16x16x64_i8 v[130:133], v[240:243], v[162:165], v[130:133]
	v_mfma_i32_16x16x64_i8 v[118:121], v[232:235], v[170:173], v[118:121]
	v_mfma_i32_16x16x64_i8 v[114:117], v[240:243], v[170:173], v[114:117]
	v_mfma_i32_16x16x64_i8 v[102:105], v[232:235], v[178:181], v[102:105]
	v_mfma_i32_16x16x64_i8 v[98:101], v[240:243], v[178:181], v[98:101]
	v_mfma_i32_16x16x64_i8 v[86:89], v[232:235], v[186:189], v[86:89]
	v_mfma_i32_16x16x64_i8 v[82:85], v[240:243], v[186:189], v[82:85]
	v_mfma_i32_16x16x64_i8 v[134:137], v[236:239], v[166:169], v[134:137]
	v_mfma_i32_16x16x64_i8 v[130:133], v[244:247], v[166:169], v[130:133]
	v_mfma_i32_16x16x64_i8 v[118:121], v[236:239], v[174:177], v[118:121]
	v_mfma_i32_16x16x64_i8 v[114:117], v[244:247], v[174:177], v[114:117]
	v_mfma_i32_16x16x64_i8 v[102:105], v[236:239], v[182:185], v[102:105]
	v_mfma_i32_16x16x64_i8 v[98:101], v[244:247], v[182:185], v[98:101]
	v_mfma_i32_16x16x64_i8 v[86:89], v[236:239], v[198:201], v[86:89]
	v_mfma_i32_16x16x64_i8 v[82:85], v[244:247], v[198:201], v[82:85]
	s_setprio 0
	s_barrier
	s_mov_b32 m0, s66
	ds_read_b128 v[202:205], v195
	ds_read_b128 v[206:209], v195 offset:1024
	ds_read_b128 v[210:213], v195 offset:2048
	ds_read_b128 v[214:217], v195 offset:3072
	global_load_lds_dwordx4 v148, s[44:45]
	s_mov_b32 m0, s67
	s_nop 0
	global_load_lds_dwordx4 v152, s[44:45]
	s_barrier
	s_waitcnt lgkmcnt(0)
	s_setprio 1
	s_waitcnt lgkmcnt(0)
	v_mfma_i32_16x16x64_i8 v[142:145], v[202:205], v[162:165], v[142:145]
	v_mfma_i32_16x16x64_i8 v[138:141], v[210:213], v[162:165], v[138:141]
	v_mfma_i32_16x16x64_i8 v[126:129], v[202:205], v[170:173], v[126:129]
	v_mfma_i32_16x16x64_i8 v[122:125], v[210:213], v[170:173], v[122:125]
	v_mfma_i32_16x16x64_i8 v[110:113], v[202:205], v[178:181], v[110:113]
	v_mfma_i32_16x16x64_i8 v[106:109], v[210:213], v[178:181], v[106:109]
	v_mfma_i32_16x16x64_i8 v[94:97], v[202:205], v[186:189], v[94:97]
	v_mfma_i32_16x16x64_i8 v[90:93], v[210:213], v[186:189], v[90:93]
	v_mfma_i32_16x16x64_i8 v[142:145], v[206:209], v[166:169], v[142:145]
	v_mfma_i32_16x16x64_i8 v[138:141], v[214:217], v[166:169], v[138:141]
	v_mfma_i32_16x16x64_i8 v[126:129], v[206:209], v[174:177], v[126:129]
	v_mfma_i32_16x16x64_i8 v[122:125], v[214:217], v[174:177], v[122:125]
	v_mfma_i32_16x16x64_i8 v[110:113], v[206:209], v[182:185], v[110:113]
	v_mfma_i32_16x16x64_i8 v[106:109], v[214:217], v[182:185], v[106:109]
	v_mfma_i32_16x16x64_i8 v[94:97], v[206:209], v[198:201], v[94:97]
	v_mfma_i32_16x16x64_i8 v[90:93], v[214:217], v[198:201], v[90:93]
	s_setprio 0
	s_mov_b32 m0, s55
	s_barrier
	ds_read_b128 v[162:165], v194 offset:16384
	ds_read_b128 v[166:169], v194 offset:17408
	ds_read_b128 v[170:173], v194 offset:18432
	ds_read_b128 v[174:177], v194 offset:19456
	ds_read_b128 v[178:181], v194 offset:20480
	ds_read_b128 v[182:185], v194 offset:21504
	ds_read_b128 v[186:189], v194 offset:22528
	ds_read_b128 v[198:201], v194 offset:23552
	global_load_lds_dwordx4 v146, s[46:47]
	s_mov_b32 m0, s56
	s_nop 0
	global_load_lds_dwordx4 v150, s[46:47]
	s_barrier
	s_waitcnt lgkmcnt(0)
	s_setprio 1
	s_waitcnt lgkmcnt(0)
	v_mfma_i32_16x16x64_i8 v[70:73], v[232:235], v[162:165], v[70:73]
	v_mfma_i32_16x16x64_i8 v[66:69], v[240:243], v[162:165], v[66:69]
	v_mfma_i32_16x16x64_i8 v[54:57], v[232:235], v[170:173], v[54:57]
	v_mfma_i32_16x16x64_i8 v[50:53], v[240:243], v[170:173], v[50:53]
	v_mfma_i32_16x16x64_i8 v[22:25], v[232:235], v[178:181], v[22:25]
	v_mfma_i32_16x16x64_i8 v[18:21], v[240:243], v[178:181], v[18:21]
	v_mfma_i32_16x16x64_i8 v[6:9], v[232:235], v[186:189], v[6:9]
	v_mfma_i32_16x16x64_i8 v[2:5], v[240:243], v[186:189], v[2:5]
	v_mfma_i32_16x16x64_i8 v[70:73], v[236:239], v[166:169], v[70:73]
	v_mfma_i32_16x16x64_i8 v[66:69], v[244:247], v[166:169], v[66:69]
	v_mfma_i32_16x16x64_i8 v[54:57], v[236:239], v[174:177], v[54:57]
	v_mfma_i32_16x16x64_i8 v[50:53], v[244:247], v[174:177], v[50:53]
	v_mfma_i32_16x16x64_i8 v[22:25], v[236:239], v[182:185], v[22:25]
	v_mfma_i32_16x16x64_i8 v[18:21], v[244:247], v[182:185], v[18:21]
	v_mfma_i32_16x16x64_i8 v[6:9], v[236:239], v[198:201], v[6:9]
	v_mfma_i32_16x16x64_i8 v[2:5], v[244:247], v[198:201], v[2:5]
	s_setprio 0
	s_barrier
	s_mov_b32 m0, s68
	s_add_u32 s0, s44, 0x44000
	s_addc_u32 s1, s45, 0
	global_load_lds_dwordx4 v148, s[0:1]
	s_mov_b32 m0, s69
	s_nop 0
	global_load_lds_dwordx4 v152, s[0:1]
	s_waitcnt vmcnt(6)
	s_barrier
; #define G_STAGE(bufoff, gbase, voff) do { _Pragma("unroll") for (int _i = 0; _i < 2; ++_i) \
;         __builtin_amdgcn_global_load_lds((const unsigned*)((const char*)(gbase) + (voff)[_i]), (LAS unsigned*)(lds + (bufoff) + ldsw + _i * 8192), 16, 0, 0); } while (0)
; #define G_WAIT_V(n) asm volatile("s_waitcnt vmcnt(" #n ")" ::: "memory")
; #define G_WAIT_L(n) asm volatile("s_waitcnt lgkmcnt(" #n ")" ::: "memory")
; #define G_BAR __builtin_amdgcn_s_barrier()
; #define G_SCHED __builtin_amdgcn_sched_barrier(0)
; template <int MODE  , class Epi, class Sched>
; __device__ __forceinline__ void gemm_phase(LAS unsigned char* lds, const GemmDesc g, const Sched& S, const Epi& E) {
;     ...
;             G_WAIT_V(6); G_BAR; G_MMA(1, 1, At, B1); G_BAR;
;             G_LDB(B0, 1, 0); G_SCHED; G_LDA(At, 1, 0); G_STAGE(G_SA(0, 1), a2 + hstepA, voffA);
;             G_WAIT_L(8); G_BAR; G_WAIT_L(0); G_MMA(0, 0, At, B0); G_BAR; G_SCHED;
;             G_LDB(B1, 1, 1); G_STAGE(G_SB(1, 0), b3, voffB);
;             G_BAR; G_WAIT_L(0); G_MMA(0, 1, At, B1); G_BAR;
	s_setprio 1
	v_mfma_i32_16x16x64_i8 v[30:33], v[202:205], v[178:181], v[30:33]
	v_mfma_i32_16x16x64_i8 v[26:29], v[210:213], v[178:181], v[26:29]
	v_mfma_i32_16x16x64_i8 v[14:17], v[202:205], v[186:189], v[14:17]
	v_mfma_i32_16x16x64_i8 v[10:13], v[210:213], v[186:189], v[10:13]
	v_mfma_i32_16x16x64_i8 v[34:37], v[202:205], v[162:165], v[78:81]
	v_mfma_i32_16x16x64_i8 v[38:41], v[210:213], v[162:165], v[74:77]
	v_mfma_i32_16x16x64_i8 v[42:45], v[202:205], v[170:173], v[62:65]
	v_mfma_i32_16x16x64_i8 v[46:49], v[210:213], v[170:173], v[58:61]
	v_mfma_i32_16x16x64_i8 v[30:33], v[206:209], v[182:185], v[30:33]
	v_mfma_i32_16x16x64_i8 v[26:29], v[214:217], v[182:185], v[26:29]
	v_mfma_i32_16x16x64_i8 v[14:17], v[206:209], v[198:201], v[14:17]
	v_mfma_i32_16x16x64_i8 v[10:13], v[214:217], v[198:201], v[10:13]
	v_mfma_i32_16x16x64_i8 v[34:37], v[206:209], v[166:169], v[34:37]
	v_mfma_i32_16x16x64_i8 v[38:41], v[214:217], v[166:169], v[38:41]
	v_mfma_i32_16x16x64_i8 v[42:45], v[206:209], v[174:177], v[42:45]
	v_mfma_i32_16x16x64_i8 v[46:49], v[214:217], v[174:177], v[46:49]
	s_setprio 0
	s_add_i32 s10, 0, 0x18000
	v_add_u32_e32 v78, s10, v191
	s_barrier
	ds_read_b128 v[58:61], v78
	ds_read_b128 v[62:65], v78 offset:1024
	ds_read_b128 v[74:77], v78 offset:2048
	ds_read_b128 v[78:81], v78 offset:3072
	s_add_u32 s0, s46, 0x44000
	s_addc_u32 s1, s47, 0
	s_mov_b32 m0, s57
	ds_read_b128 v[162:165], v194 offset:32768
	ds_read_b128 v[166:169], v194 offset:33792
	ds_read_b128 v[170:173], v194 offset:34816
	ds_read_b128 v[174:177], v194 offset:35840
	ds_read_b128 v[178:181], v194 offset:36864
	ds_read_b128 v[182:185], v194 offset:37888
	ds_read_b128 v[186:189], v194 offset:38912
	ds_read_b128 v[198:201], v194 offset:39936
	global_load_lds_dwordx4 v146, s[0:1]
	s_mov_b32 m0, s58
	s_nop 0
	global_load_lds_dwordx4 v150, s[0:1]
	s_waitcnt lgkmcnt(8)
	s_barrier
	s_waitcnt lgkmcnt(0)
	s_setprio 1
	s_waitcnt lgkmcnt(0)
	v_mfma_i32_16x16x64_i8 v[134:137], v[58:61], v[162:165], v[134:137]
	v_mfma_i32_16x16x64_i8 v[130:133], v[74:77], v[162:165], v[130:133]
	v_mfma_i32_16x16x64_i8 v[118:121], v[58:61], v[170:173], v[118:121]
	v_mfma_i32_16x16x64_i8 v[114:117], v[74:77], v[170:173], v[114:117]
	v_mfma_i32_16x16x64_i8 v[102:105], v[58:61], v[178:181], v[102:105]
	v_mfma_i32_16x16x64_i8 v[98:101], v[74:77], v[178:181], v[98:101]
	v_mfma_i32_16x16x64_i8 v[86:89], v[58:61], v[186:189], v[86:89]
	v_mfma_i32_16x16x64_i8 v[82:85], v[74:77], v[186:189], v[82:85]
	v_mfma_i32_16x16x64_i8 v[134:137], v[62:65], v[166:169], v[134:137]
	v_mfma_i32_16x16x64_i8 v[130:133], v[78:81], v[166:169], v[130:133]
	v_mfma_i32_16x16x64_i8 v[118:121], v[62:65], v[174:177], v[118:121]
	v_mfma_i32_16x16x64_i8 v[114:117], v[78:81], v[174:177], v[114:117]
	v_mfma_i32_16x16x64_i8 v[102:105], v[62:65], v[182:185], v[102:105]
	v_mfma_i32_16x16x64_i8 v[98:101], v[78:81], v[182:185], v[98:101]
	v_mfma_i32_16x16x64_i8 v[86:89], v[62:65], v[198:201], v[86:89]
	v_mfma_i32_16x16x64_i8 v[82:85], v[78:81], v[198:201], v[82:85]
	s_setprio 0
	s_barrier
	s_add_i32 s11, 0, 0x1c000
	s_add_i32 s0, s10, s54
	v_add_u32_e32 v154, s11, v191
	s_add_u32 s98, s44, 0x80
	s_addc_u32 s99, s45, 0
	s_mov_b32 m0, s0
	ds_read_b128 v[202:205], v154
	ds_read_b128 v[206:209], v154 offset:1024
	ds_read_b128 v[210:213], v154 offset:2048
	ds_read_b128 v[214:217], v154 offset:3072
	global_load_lds_dwordx4 v148, s[98:99]
	s_add_i32 m0, s0, 0x2000
	s_nop 0
	global_load_lds_dwordx4 v152, s[98:99]
	s_barrier
; #define G_STAGE(bufoff, gbase, voff) do { _Pragma("unroll") for (int _i = 0; _i < 2; ++_i) \
;         __builtin_amdgcn_global_load_lds((const unsigned*)((const char*)(gbase) + (voff)[_i]), (LAS unsigned*)(lds + (bufoff) + ldsw + _i * 8192), 16, 0, 0); } while (0)
; #define G_WAIT_V(n) asm volatile("s_waitcnt vmcnt(" #n ")" ::: "memory")
; #define G_WAIT_L(n) asm volatile("s_waitcnt lgkmcnt(" #n ")" ::: "memory")
; #define G_BAR __builtin_amdgcn_s_barrier()
; #define G_SCHED __builtin_amdgcn_sched_barrier(0)
; template <int MODE  , class Epi, class Sched>
; __device__ __forceinline__ void gemm_phase(LAS unsigned char* lds, const GemmDesc g, const Sched& S, const Epi& E) {
;     ...
;             G_LDB(B1, 1, 1); G_STAGE(G_SB(1, 0), b3, voffB);
;             G_BAR; G_WAIT_L(0); G_MMA(0, 1, At, B1); G_BAR;
;             G_LDA(At, 1, 1); G_STAGE(G_SA(1, 0), a3, voffA);
;             G_BAR; G_WAIT_L(0); G_MMA(1, 0, At, B0); G_BAR; G_SCHED;
;             G_STAGE(G_SB(1, 1), b3 + hstepB, voffB);
;             G_WAIT_V(6); G_BAR; G_MMA(1, 1, At, B1); G_BAR;
;         }
	s_waitcnt lgkmcnt(0)
	s_setprio 1
	s_waitcnt lgkmcnt(0)
	v_mfma_i32_16x16x64_i8 v[142:145], v[202:205], v[162:165], v[142:145]
	v_mfma_i32_16x16x64_i8 v[138:141], v[210:213], v[162:165], v[138:141]
	v_mfma_i32_16x16x64_i8 v[126:129], v[202:205], v[170:173], v[126:129]
	v_mfma_i32_16x16x64_i8 v[122:125], v[210:213], v[170:173], v[122:125]
	v_mfma_i32_16x16x64_i8 v[110:113], v[202:205], v[178:181], v[110:113]
	v_mfma_i32_16x16x64_i8 v[106:109], v[210:213], v[178:181], v[106:109]
	v_mfma_i32_16x16x64_i8 v[94:97], v[202:205], v[186:189], v[94:97]
	v_mfma_i32_16x16x64_i8 v[90:93], v[210:213], v[186:189], v[90:93]
	v_mfma_i32_16x16x64_i8 v[142:145], v[206:209], v[166:169], v[142:145]
	v_mfma_i32_16x16x64_i8 v[138:141], v[214:217], v[166:169], v[138:141]
	v_mfma_i32_16x16x64_i8 v[126:129], v[206:209], v[174:177], v[126:129]
	v_mfma_i32_16x16x64_i8 v[122:125], v[214:217], v[174:177], v[122:125]
	v_mfma_i32_16x16x64_i8 v[110:113], v[206:209], v[182:185], v[110:113]
	v_mfma_i32_16x16x64_i8 v[106:109], v[214:217], v[182:185], v[106:109]
	v_mfma_i32_16x16x64_i8 v[94:97], v[206:209], v[198:201], v[94:97]
	v_mfma_i32_16x16x64_i8 v[90:93], v[214:217], v[198:201], v[90:93]
	s_setprio 0
	s_mov_b32 m0, s60
	s_barrier
	ds_read_b128 v[162:165], v194 offset:49152
	ds_read_b128 v[166:169], v194 offset:50176
	ds_read_b128 v[170:173], v194 offset:51200
	ds_read_b128 v[174:177], v194 offset:52224
	ds_read_b128 v[178:181], v194 offset:53248
	ds_read_b128 v[182:185], v194 offset:54272
	ds_read_b128 v[186:189], v194 offset:55296
	ds_read_b128 v[198:201], v194 offset:56320
	s_add_u32 s98, s46, 0x80
	s_addc_u32 s99, s47, 0
	global_load_lds_dwordx4 v146, s[98:99]
	s_mov_b32 m0, s61
	s_nop 0
	global_load_lds_dwordx4 v150, s[98:99]
	s_waitcnt vmcnt(10)
	s_barrier
	s_waitcnt lgkmcnt(0)
	s_setprio 1
	s_waitcnt lgkmcnt(0)
	v_mfma_i32_16x16x64_i8 v[70:73], v[58:61], v[162:165], v[70:73]
	v_mfma_i32_16x16x64_i8 v[66:69], v[74:77], v[162:165], v[66:69]
	v_mfma_i32_16x16x64_i8 v[54:57], v[58:61], v[170:173], v[54:57]
	v_mfma_i32_16x16x64_i8 v[50:53], v[74:77], v[170:173], v[50:53]
	v_mfma_i32_16x16x64_i8 v[22:25], v[58:61], v[178:181], v[22:25]
	v_mfma_i32_16x16x64_i8 v[18:21], v[74:77], v[178:181], v[18:21]
	v_mfma_i32_16x16x64_i8 v[6:9], v[58:61], v[186:189], v[6:9]
	v_mfma_i32_16x16x64_i8 v[2:5], v[74:77], v[186:189], v[2:5]
	v_mfma_i32_16x16x64_i8 v[70:73], v[62:65], v[166:169], v[70:73]
	v_mfma_i32_16x16x64_i8 v[66:69], v[78:81], v[166:169], v[66:69]
	v_mfma_i32_16x16x64_i8 v[54:57], v[62:65], v[174:177], v[54:57]
	v_mfma_i32_16x16x64_i8 v[50:53], v[78:81], v[174:177], v[50:53]
	v_mfma_i32_16x16x64_i8 v[22:25], v[62:65], v[182:185], v[22:25]
	v_mfma_i32_16x16x64_i8 v[18:21], v[78:81], v[182:185], v[18:21]
	v_mfma_i32_16x16x64_i8 v[6:9], v[62:65], v[198:201], v[6:9]
	v_mfma_i32_16x16x64_i8 v[2:5], v[78:81], v[198:201], v[2:5]
	s_setprio 0
	s_barrier
	ds_read_b128 v[232:235], v193
	ds_read_b128 v[236:239], v193 offset:1024
	ds_read_b128 v[240:243], v193 offset:2048
	ds_read_b128 v[244:247], v193 offset:3072
	s_add_u32 s0, s44, 0x44080
	s_addc_u32 s1, s45, 0
	s_add_i32 s10, s11, s54
	s_mov_b32 m0, s10
	s_nop 0
	global_load_lds_dwordx4 v148, s[0:1]
	s_add_i32 m0, s10, 0x2000
	s_nop 0
	global_load_lds_dwordx4 v152, s[0:1]
	s_waitcnt vmcnt(6)
	s_barrier
	s_setprio 1
	v_mfma_i32_16x16x64_i8 v[34:37], v[202:205], v[162:165], v[34:37]
	s_add_i32 s77, s77, 2
	s_add_u32 s72, s72, 0x100
	s_addc_u32 s76, s76, 0
	s_cmp_gt_u32 s77, 13
	s_mov_b64 s[34:35], s[40:41]
	v_mfma_i32_16x16x64_i8 v[78:81], v[206:209], v[166:169], v[34:37]
	v_mfma_i32_16x16x64_i8 v[34:37], v[210:213], v[162:165], v[38:41]
	v_mfma_i32_16x16x64_i8 v[74:77], v[214:217], v[166:169], v[34:37]
	v_mfma_i32_16x16x64_i8 v[34:37], v[202:205], v[170:173], v[42:45]
	v_mfma_i32_16x16x64_i8 v[62:65], v[206:209], v[174:177], v[34:37]
	v_mfma_i32_16x16x64_i8 v[34:37], v[210:213], v[170:173], v[46:49]
	v_mfma_i32_16x16x64_i8 v[30:33], v[202:205], v[178:181], v[30:33]
	v_mfma_i32_16x16x64_i8 v[26:29], v[210:213], v[178:181], v[26:29]
	v_mfma_i32_16x16x64_i8 v[14:17], v[202:205], v[186:189], v[14:17]
	v_mfma_i32_16x16x64_i8 v[10:13], v[210:213], v[186:189], v[10:13]
	v_mfma_i32_16x16x64_i8 v[58:61], v[214:217], v[174:177], v[34:37]
	v_mfma_i32_16x16x64_i8 v[30:33], v[206:209], v[182:185], v[30:33]
	v_mfma_i32_16x16x64_i8 v[26:29], v[214:217], v[182:185], v[26:29]
	v_mfma_i32_16x16x64_i8 v[14:17], v[206:209], v[198:201], v[14:17]
	v_mfma_i32_16x16x64_i8 v[10:13], v[214:217], v[198:201], v[10:13]
	s_setprio 0
	s_cbranch_scc1 .Lkdone_p1c
	s_barrier
	s_branch .LBB0_527
